# v112 plus GEMM prologue de-serialisation and OUT tail-entry store drain removed
# speedup vs baseline: 1.0093x; 1.0093x over previous
;     __host__ __device__ bool next(int i, Unit& u) const { if (i != 0 || S.c >= 2 * (S.nwg - base)) return false; S.unit_of(base + (S.c >> 1), u); u.hm = S.c & 1; return true; }
; #define PG8_STAGE(bufoff, gbase) do { _Pragma("unroll") for (int _i = 0; _i < 2; ++_i) \
;         __builtin_amdgcn_global_load_lds((const unsigned*)((const char*)(gbase) + voffA[_i]), (LAS unsigned*)(lds + (bufoff) + ldsw + _i * 8192), 16, 0, 0); } while (0)
; #define PG8_WAIT_V(n) asm volatile("s_waitcnt vmcnt(" #n ")" ::: "memory")
; #define PG8_BAR __builtin_amdgcn_s_barrier()
; template <class Epi, bool ALIGN_EPI, bool SP2, bool BF = false, bool HALFM = false, class Order = StaticOrder>
; __device__ __forceinline__ void gemm_phase(LAS unsigned char* lds, const int tid, const Gemm g, const Order& S, const Epi& E, const bool dry = false) {
;     ...
;     for (int i = 0; i < 2; ++i) { int R, C; stage_rc(tid * 16 + i * 8192, R, C); voffA[i] = (unsigned)(R * K + C) * 2u; }
;     const size_t kstep = (size_t)(BK * 2);
;     const size_t hstep = (size_t)HALF * K * 2;
;     const size_t tstep = 2 * hstep;
;     const unsigned ldsw = (unsigned)wid * 1024u;
;     const int aoff = lds_byte(wr * 64 + fr, fq * 8), boff = lds_byte(wc * 32 + fr, fq * 8);
;     ...
;     Unit cur, nxt; int ui = 0;
;     if (!S.next(0, cur)) return;
;     f32x4 acc[2][2][4][2];
; #pragma unroll
;     for (int a = 0; a < 2; ++a)
; #pragma unroll
;         for (int b = 0; b < 2; ++b)
; #pragma unroll
;             for (int m = 0; m < 4; ++m)
; #pragma unroll
;                 for (int n = 0; n < 2; ++n) acc[a][b][m][n] = (f32x4){0.f, 0.f, 0.f, 0.f};
;     h16x8 At[4][2], B0[2][2], B1[2][2];
;     const char* cA = (const char*)g.A + (size_t)cur.pm * tstep + (HALFM ? (size_t)cur.hm * hstep : (size_t)0); const char* cB = (const char*)g.Bt + (size_t)cur.pn * tstep;
;     if constexpr (SP2) {
;         PG8_STAGE(PG8_SB(0, 0), cB); PG8_STAGE(PG8_SB(0, 1), cB + hstep); PG8_STAGE(PG8_SA(0, 0), cA); PG8_STAGE(PG8_SA(0, 1), cA + hstep);
;         if (wr == 1) PG8_BAR;
;         PG8_WAIT_V(2); PG8_BAR;
;         PG8_STAGE(PG8_SB(1, 0), cB + kstep); PG8_STAGE(PG8_SA(1, 0), cA + kstep); PG8_STAGE(PG8_SB(1, 1), cB + hstep + kstep);
;         PG8_WAIT_V(6); PG8_BAR;
.LBB0_555:
	s_lshl_b32 s12, s66, 4
	s_mul_i32 s3, s66, 0x3b800
	s_lshl_b32 s0, s66, 6
	s_ashr_i32 s13, s12, 31
	v_readlane_b32 s56, v252, 28
	s_ashr_i32 s1, s0, 31
	s_lshl_b64 s[12:13], s[12:13], 2
	v_readlane_b32 s64, v252, 36
	v_bfe_u32 v197, v246, 4, 2
	v_readlane_b32 s65, v252, 37
	s_add_u32 s12, s64, s12
	v_and_b32_e32 v196, 15, v246
	v_lshlrev_b32_e32 v16, 4, v197
	v_lshlrev_b32_e32 v17, 2, v246
	s_addc_u32 s13, s65, s13
	s_and_b32 s76, s10, 3
	v_lshl_or_b32 v16, v196, 6, v16
	s_lshl_b32 s5, s11, 13
	v_and_b32_e32 v17, 32, v17
	s_add_i32 s79, s74, 0x18000
	v_bitop3_b32 v18, v16, s5, v17 bitop3:0xde
	s_lshl_b32 s5, s76, 12
	s_add_i32 s80, s79, s9
	s_lshl_b32 s77, s11, 6
	v_bitop3_b32 v198, s5, v16, v17 bitop3:0xf6
	s_add_i32 s5, s74, 0x20400
	v_lshl_add_u64 v[8:9], v[8:9], 0, s[94:95]
	s_mov_b32 m0, s80
	s_add_i32 s81, s80, 0x2000
	s_add_i32 s82, s52, 0x8000
	s_add_i32 s83, s52, 0xa000
	global_load_lds_dwordx4 v[8:9], off
	v_lshl_add_u64 v[6:7], v[6:7], 0, s[94:95]
	s_mov_b32 m0, s81
	s_add_u32 s10, s36, 0x40080
	global_load_lds_dwordx4 v[6:7], off
	v_lshl_add_u64 v[2:3], v[2:3], 0, s[94:95]
	s_mov_b32 m0, s82
	s_addc_u32 s11, s37, 0
	s_add_i32 s84, s74, 0x1c000
	global_load_lds_dwordx4 v[2:3], off
	v_lshl_add_u64 v[2:3], v[4:5], 0, s[94:95]
	s_mov_b32 m0, s83
	s_add_i32 s85, s84, s9
	global_load_lds_dwordx4 v[2:3], off
	v_lshl_add_u64 v[2:3], s[10:11], 0, v[0:1]
	s_mov_b32 m0, s85
	s_add_i32 s86, s85, 0x2000
	global_load_lds_dwordx4 v[2:3], off
	v_lshl_add_u64 v[2:3], s[10:11], 0, v[164:165]
	s_mov_b32 m0, s86
	v_writelane_b32 v253, s12, 5
	global_load_lds_dwordx4 v[2:3], off
	s_waitcnt vmcnt(8)
	s_barrier
	v_lshlrev_b32_e32 v2, 14, v13
	v_and_b32_e32 v2, 0xffff8000, v2
	v_writelane_b32 v253, s13, 6
	v_lshl_add_u32 v2, v14, 11, v2
	v_and_b32_e32 v3, 1, v13
	v_writelane_b32 v253, s5, 7
	v_lshl_or_b32 v2, v3, 6, v2
	s_cmpk_lt_u32 s8, 0x100
	v_readlane_b32 s8, v253, 0
	v_lshl_add_u32 v166, v15, 1, v2
	v_lshlrev_b32_e32 v2, 14, v10
	s_cselect_b64 s[12:13], -1, 0
	s_lshl_b32 s5, s76, 7
	s_ashr_i32 s87, s73, 31
	v_readlane_b32 s9, v253, 1
	v_and_b32_e32 v2, 0xffff8000, v2
	v_readlane_b32 s70, v252, 42
	v_readlane_b32 s71, v252, 43
	s_waitcnt vmcnt(6)
	s_cmp_eq_u64 s[8:9], 0
	v_lshl_add_u32 v2, v11, 11, v2
	v_and_b32_e32 v3, 1, v10
	s_cselect_b64 s[14:15], -1, 0
	s_or_b32 s96, s3, s5
	s_add_i32 s3, s74, 0x21400
	v_lshl_or_b32 v2, v3, 6, v2
	v_readlane_b32 s70, v252, 58
	s_add_i32 s96, s96, 0x2680000
	v_writelane_b32 v253, s3, 8
	v_mov_b32_e32 v167, v1
	v_lshl_add_u32 v168, v12, 1, v2
	v_mov_b32_e32 v169, v1
	s_mov_b32 s10, 0
	v_add_u32_e32 v199, s74, v18
	s_lshl_b64 s[16:17], s[0:1], 2
	v_readlane_b32 s71, v252, 59
	v_readlane_b32 s57, v252, 29
	v_readlane_b32 s58, v252, 30
	v_readlane_b32 s59, v252, 31
	v_readlane_b32 s60, v252, 32
	v_readlane_b32 s61, v252, 33
	v_readlane_b32 s62, v252, 34
	v_readlane_b32 s63, v252, 35
	v_readlane_b32 s66, v252, 38
	v_readlane_b32 s67, v252, 39
	v_readlane_b32 s68, v252, 40
	v_readlane_b32 s69, v252, 41
	s_barrier
	s_mov_b32 s100, 0
	s_branch .LBB0_558
	s_nop 0
